# up epilogue: conv weight/bias loads hoisted to the epilogue head (into vacated prefetch regs), on top of prefetch+xg merge
# baseline (speedup 1.0000x reference)
;     __device__ __forceinline__ void operator()(f32x4 (&acc)[2][2][4][2], const Unit& u, int wr, int wc, int fr, int fq) const {
;     ...
;             const int tq = tok0 + 8 * fr; const int tA = tq < 0 ? 0 : (tq > TOK - 1 ? TOK - 1 : tq), tB = (tq + 7) > TOK - 1 ? TOK - 1 : (tq + 7);
;             const int bA = batch_of(tA), bB = batch_of(tB); const bool same = __all(bA == bB);
;             const float* bp0 = bias + 256 * u.pn + 32 * wc + 8 * fq;
;             f32x4 bvA[2][2]; float sq[8];
; #pragma unroll
;             for (int am = 0; am < 8; ++am) { int tok = tq + am; tok = tok < 0 ? 0 : (tok > TOK - 1 ? TOK - 1 : tok); sq[am] = LDG(float, ssq + tok); }
; #pragma unroll
;             for (int bj = 0; bj < 2; ++bj)
; #pragma unroll
;                 for (int n = 0; n < 2; ++n) bvA[bj][n] = LDG(f32x4, bp0 + (size_t)bA * (2 * DFF) + bj * HALF + 4 * n);
; #pragma unroll
;             for (int am = 0; am < 8; ++am) { const int ai = am >> 2, m = am & 3;
;                 const float rs = __builtin_amdgcn_rsqf(sq[am] * (1.f / DM) + EPS);
; #pragma unroll
;                 for (int bj = 0; bj < 2; ++bj)
; #pragma unroll
;                     for (int n = 0; n < 2; ++n) acc[ai][bj][m][n] = acc[ai][bj][m][n] * rs + bvA[bj][n];
;                 asm volatile("" : "+v"(acc[ai][0][m][0]), "+v"(acc[ai][0][m][1]), "+v"(acc[ai][1][m][0]), "+v"(acc[ai][1][m][1])); }
;     ...
;         for (int n = 0; n < 2; ++n) { w0[n] = LDG(f32x4, cw + f0 + 4 * n); w1[n] = LDG(f32x4, cw + DFF + f0 + 4 * n); w2[n] = LDG(f32x4, cw + 2 * DFF + f0 + 4 * n); cbv[n] = LDG(f32x4, cb + f0 + 4 * n); }
.LBB0_1302:
	s_mul_i32 s4, s26, 0xfc
	v_add_u32_e32 v203, s4, v197
	v_med3_i32 v130, v203, 0, v238
	v_add_u32_e32 v132, 0xffffe000, v130
	v_lshrrev_b32_e32 v132, 12, v132
	s_movk_i32 s4, 0x2000
	v_add_u32_e32 v214, 1, v203
	v_add_u32_e32 v207, 3, v203
	v_lshrrev_b32_e32 v131, 11, v130
	v_add_u32_e32 v132, 4, v132
	v_cmp_gt_i32_e32 vcc, s4, v203
	s_lshl_b32 s4, s92, 8
	v_lshlrev_b32_e32 v130, 2, v130
	v_med3_i32 v212, v214, 0, v238
	v_add_u32_e32 v208, 2, v203
	v_med3_i32 v210, v207, 0, v238
	v_cndmask_b32_e32 v192, v132, v131, vcc
	s_ashr_i32 s5, s4, 31
	v_mov_b32_e32 v132, v224
	v_lshlrev_b32_e32 v130, 2, v212
	v_med3_i32 v211, v208, 0, v238
	v_lshlrev_b32_e32 v133, 2, v210
	v_lshlrev_b32_e32 v131, 2, v211
	v_mov_b32_e32 v134, v228
	v_mov_b32_e32 v135, v231
	s_nop 0
	v_mov_b32_e32 v133, v233
	v_lshl_add_u64 v[190:191], s[4:5], 2, v[184:185]
	v_add_u32_e32 v206, 4, v203
	v_add_u32_e32 v202, 7, v203
	v_mad_u64_u32 v[130:131], s[4:5], v192, s15, v[190:191]
	v_med3_i32 v209, v206, 0, v238
	v_add_u32_e32 v205, 5, v203
	v_med3_i32 v193, v202, 0, v238
	v_mov_b64_e32 v[174:175], v[240:241]
	v_mov_b64_e32 v[176:177], v[242:243]
	v_mov_b64_e32 v[170:171], v[244:245]
	v_mov_b64_e32 v[172:173], v[246:247]
	v_mov_b64_e32 v[166:167], v[248:249]
	v_mov_b64_e32 v[168:169], v[250:251]
	v_mov_b64_e32 v[162:163], v[222:223]
	v_mov_b64_e32 v[164:165], v[236:237]
	v_lshlrev_b32_e32 v130, 2, v209
	v_med3_i32 v195, v205, 0, v238
	v_add_u32_e32 v204, 6, v203
	v_lshlrev_b32_e32 v136, 2, v193
	v_mov_b32_e32 v215, v234
	v_mov_b32_e32 v220, v253
	v_lshlrev_b32_e32 v130, 2, v195
	v_med3_i32 v194, v204, 0, v238
	v_mov_b32_e32 v217, v239
	v_lshlrev_b32_e32 v130, 2, v194
	v_mov_b32_e32 v219, v252
	v_min_i32_e32 v130, 0x9ff8, v203
	v_add_u32_e32 v131, 7, v130
	v_add_u32_e32 v130, 0xffffe007, v130
	v_lshrrev_b32_e32 v130, 12, v130
	s_movk_i32 s4, 0x1ff9
	v_ashrrev_i32_e32 v131, 11, v131
	v_add_u32_e32 v130, 4, v130
	v_cmp_gt_i32_e64 s[42:43], s4, v203
	s_waitcnt vmcnt(0)
	v_lshl_or_b32 v221, s92, 7, v200
	v_lshlrev_b32_e32 v221, 2, v221
	global_load_dwordx4 v[240:243], v221, s[58:59] offset:16
	global_load_dwordx4 v[244:247], v221, s[60:61] offset:16
	global_load_dwordx4 v[248:251], v221, s[54:55] offset:16
	global_load_dwordx2 v[222:223], v221, s[58:59]
	global_load_dwordx2 v[236:237], v221, s[58:59] offset:8
	global_load_dwordx2 v[252:253], v221, s[54:55]
	global_load_dword v224, v221, s[54:55] offset:8
	global_load_dword v228, v221, s[54:55] offset:12
	global_load_dword v231, v221, s[52:53] offset:16
	global_load_dword v233, v221, s[52:53] offset:20
	global_load_dword v234, v221, s[52:53] offset:24
	global_load_dword v239, v221, s[52:53] offset:28
	v_fmamk_f32 v133, v133, 0x3a000000, v226
	v_cndmask_b32_e64 v213, v130, v131, s[42:43]
	v_fmamk_f32 v130, v132, 0x3a000000, v226
	v_fmamk_f32 v131, v134, 0x3a000000, v226
	v_rsq_f32_e32 v130, v130
	v_rsq_f32_e32 v132, v131
	v_rsq_f32_e32 v218, v133
	v_fmamk_f32 v134, v135, 0x3a000000, v226
	v_pk_fma_f32 v[150:151], v[126:127], v[130:131], v[174:175] op_sel_hi:[1,0,1]
	v_pk_fma_f32 v[126:127], v[114:115], v[132:133], v[170:171] op_sel_hi:[1,0,1]
	v_rsq_f32_e32 v216, v134
	v_pk_fma_f32 v[142:143], v[122:123], v[130:131], v[170:171] op_sel_hi:[1,0,1]
	v_pk_fma_f32 v[152:153], v[128:129], v[130:131], v[176:177] op_sel_hi:[1,0,1]
	v_pk_fma_f32 v[128:129], v[116:117], v[132:133], v[172:173] op_sel_hi:[1,0,1]
	v_pk_fma_f32 v[144:145], v[124:125], v[130:131], v[172:173] op_sel_hi:[1,0,1]
	v_cmp_eq_u32_e64 s[44:45], v192, v213
	v_pk_fma_f32 v[160:161], v[108:109], v[130:131], v[168:169] op_sel_hi:[1,0,1]
	v_pk_fma_f32 v[158:159], v[106:107], v[130:131], v[166:167] op_sel_hi:[1,0,1]
	global_load_dwordx4 v[106:109], v221, s[52:53]
	v_pk_fma_f32 v[122:123], v[62:63], v[216:217], v[162:163] op_sel_hi:[1,0,1]
	v_pk_fma_f32 v[124:125], v[64:65], v[216:217], v[164:165] op_sel_hi:[1,0,1]
	v_pk_fma_f32 v[114:115], v[78:79], v[218:219], v[166:167] op_sel_hi:[1,0,1]
	v_fmamk_f32 v78, v215, 0x3a000000, v226
	v_rsq_f32_e32 v78, v78
	v_pk_fma_f32 v[62:63], v[82:83], v[218:219], v[170:171] op_sel_hi:[1,0,1]
	v_pk_fma_f32 v[82:83], v[66:67], v[218:219], v[162:163] op_sel_hi:[1,0,1]
	v_pk_fma_f32 v[116:117], v[80:81], v[218:219], v[168:169] op_sel_hi:[1,0,1]
	v_pk_fma_f32 v[66:67], v[58:59], v[78:79], v[166:167] op_sel_hi:[1,0,1]
	v_fmamk_f32 v58, v217, 0x3a000000, v226
	v_rsq_f32_e32 v80, v58
	v_pk_fma_f32 v[58:59], v[30:31], v[78:79], v[162:163] op_sel_hi:[1,0,1]
	v_pk_fma_f32 v[64:65], v[84:85], v[218:219], v[172:173] op_sel_hi:[1,0,1]
	v_pk_fma_f32 v[84:85], v[68:69], v[218:219], v[164:165] op_sel_hi:[1,0,1]
	v_pk_fma_f32 v[30:31], v[50:51], v[80:81], v[170:171] op_sel_hi:[1,0,1]
	v_pk_fma_f32 v[50:51], v[42:43], v[80:81], v[166:167] op_sel_hi:[1,0,1]
	v_fmamk_f32 v42, v219, 0x3a000000, v226
	v_pk_fma_f32 v[56:57], v[56:57], v[78:79], v[176:177] op_sel_hi:[1,0,1]
	v_pk_fma_f32 v[54:55], v[54:55], v[78:79], v[174:175] op_sel_hi:[1,0,1]
	v_pk_fma_f32 v[48:49], v[48:49], v[78:79], v[172:173] op_sel_hi:[1,0,1]
	v_pk_fma_f32 v[46:47], v[46:47], v[78:79], v[170:171] op_sel_hi:[1,0,1]
	v_pk_fma_f32 v[68:69], v[60:61], v[78:79], v[168:169] op_sel_hi:[1,0,1]
	v_pk_fma_f32 v[60:61], v[32:33], v[78:79], v[164:165] op_sel_hi:[1,0,1]
	v_rsq_f32_e32 v78, v42
	v_pk_fma_f32 v[42:43], v[6:7], v[80:81], v[162:163] op_sel_hi:[1,0,1]
	v_pk_fma_f32 v[40:41], v[40:41], v[80:81], v[176:177] op_sel_hi:[1,0,1]
	v_pk_fma_f32 v[38:39], v[38:39], v[80:81], v[174:175] op_sel_hi:[1,0,1]
	v_pk_fma_f32 v[6:7], v[34:35], v[78:79], v[170:171] op_sel_hi:[1,0,1]
	v_pk_fma_f32 v[34:35], v[26:27], v[78:79], v[166:167] op_sel_hi:[1,0,1]
	v_fmamk_f32 v26, v220, 0x3a000000, v226
;     __device__ __forceinline__ void operator()(f32x4 (&acc)[2][2][4][2], const Unit& u, int wr, int wc, int fr, int fq) const {
;     ...
; #pragma unroll
;                     for (int n = 0; n < 2; ++n) acc[ai][bj][m][n] = acc[ai][bj][m][n] * rs + bvA[bj][n];
;                 asm volatile("" : "+v"(acc[ai][0][m][0]), "+v"(acc[ai][0][m][1]), "+v"(acc[ai][1][m][0]), "+v"(acc[ai][1][m][1])); }
;             if (!same) {
;                 asm volatile("" ::: "memory");
;                 f32x4 dv[2][2];
; #pragma unroll
;                 for (int bj = 0; bj < 2; ++bj)
; #pragma unroll
;                     for (int n = 0; n < 2; ++n) dv[bj][n] = LDG(f32x4, bp0 + (size_t)bB * (2 * DFF) + bj * HALF + 4 * n) - bvA[bj][n];
; #pragma unroll
;                 for (int am = 0; am < 8; ++am) { const int ai = am >> 2, m = am & 3; int tok = tq + am; tok = tok < 0 ? 0 : (tok > TOK - 1 ? TOK - 1 : tok);
;                     const float mB = (batch_of(tok) == bA) ? 0.f : 1.f;
; #pragma unroll
;                     for (int bj = 0; bj < 2; ++bj)
; #pragma unroll
;                         for (int n = 0; n < 2; ++n) acc[ai][bj][m][n] += dv[bj][n] * mB; } } }
;         f32x4 w0[2], w1[2], w2[2], cbv[2];
; #pragma unroll
;         for (int n = 0; n < 2; ++n) { w0[n] = LDG(f32x4, cw + f0 + 4 * n); w1[n] = LDG(f32x4, cw + DFF + f0 + 4 * n); w2[n] = LDG(f32x4, cw + 2 * DFF + f0 + 4 * n); cbv[n] = LDG(f32x4, cb + f0 + 4 * n); }
	v_pk_fma_f32 v[32:33], v[52:53], v[80:81], v[172:173] op_sel_hi:[1,0,1]
	v_pk_fma_f32 v[52:53], v[44:45], v[80:81], v[168:169] op_sel_hi:[1,0,1]
	v_pk_fma_f32 v[44:45], v[8:9], v[80:81], v[164:165] op_sel_hi:[1,0,1]
	v_rsq_f32_e32 v80, v26
	v_pk_fma_f32 v[156:157], v[100:101], v[130:131], v[164:165] op_sel_hi:[1,0,1]
	v_pk_fma_f32 v[154:155], v[98:99], v[130:131], v[162:163] op_sel_hi:[1,0,1]
	v_pk_fma_f32 v[136:137], v[120:121], v[132:133], v[176:177] op_sel_hi:[1,0,1]
	v_pk_fma_f32 v[134:135], v[118:119], v[132:133], v[174:175] op_sel_hi:[1,0,1]
	v_pk_fma_f32 v[148:149], v[96:97], v[132:133], v[168:169] op_sel_hi:[1,0,1]
	v_pk_fma_f32 v[146:147], v[94:95], v[132:133], v[166:167] op_sel_hi:[1,0,1]
	v_pk_fma_f32 v[140:141], v[88:89], v[132:133], v[164:165] op_sel_hi:[1,0,1]
	v_pk_fma_f32 v[138:139], v[86:87], v[132:133], v[162:163] op_sel_hi:[1,0,1]
	v_pk_fma_f32 v[120:121], v[112:113], v[216:217], v[176:177] op_sel_hi:[1,0,1]
	v_pk_fma_f32 v[118:119], v[110:111], v[216:217], v[174:175] op_sel_hi:[1,0,1]
	v_pk_fma_f32 v[96:97], v[104:105], v[216:217], v[172:173] op_sel_hi:[1,0,1]
	v_pk_fma_f32 v[94:95], v[102:103], v[216:217], v[170:171] op_sel_hi:[1,0,1]
	global_load_dwordx4 v[102:105], v221, s[60:61]
	v_pk_fma_f32 v[132:133], v[72:73], v[216:217], v[168:169] op_sel_hi:[1,0,1]
	v_pk_fma_f32 v[130:131], v[70:71], v[216:217], v[166:167] op_sel_hi:[1,0,1]
	v_pk_fma_f32 v[72:73], v[92:93], v[218:219], v[176:177] op_sel_hi:[1,0,1]
	v_pk_fma_f32 v[70:71], v[90:91], v[218:219], v[174:175] op_sel_hi:[1,0,1]
	v_pk_fma_f32 v[20:21], v[20:21], v[78:79], v[176:177] op_sel_hi:[1,0,1]
	v_pk_fma_f32 v[18:19], v[18:19], v[78:79], v[174:175] op_sel_hi:[1,0,1]
	v_pk_fma_f32 v[8:9], v[36:37], v[78:79], v[172:173] op_sel_hi:[1,0,1]
	v_pk_fma_f32 v[36:37], v[28:29], v[78:79], v[168:169] op_sel_hi:[1,0,1]
	v_pk_fma_f32 v[28:29], v[12:13], v[78:79], v[164:165] op_sel_hi:[1,0,1]
	v_pk_fma_f32 v[26:27], v[10:11], v[78:79], v[162:163] op_sel_hi:[1,0,1]
	v_pk_fma_f32 v[24:25], v[24:25], v[80:81], v[176:177] op_sel_hi:[1,0,1]
	v_pk_fma_f32 v[22:23], v[22:23], v[80:81], v[174:175] op_sel_hi:[1,0,1]
	v_pk_fma_f32 v[12:13], v[76:77], v[80:81], v[172:173] op_sel_hi:[1,0,1]
	v_pk_fma_f32 v[10:11], v[74:75], v[80:81], v[170:171] op_sel_hi:[1,0,1]
	v_pk_fma_f32 v[16:17], v[16:17], v[80:81], v[168:169] op_sel_hi:[1,0,1]
	v_pk_fma_f32 v[14:15], v[14:15], v[80:81], v[166:167] op_sel_hi:[1,0,1]
	v_pk_fma_f32 v[4:5], v[4:5], v[80:81], v[164:165] op_sel_hi:[1,0,1]
	v_pk_fma_f32 v[2:3], v[2:3], v[80:81], v[162:163] op_sel_hi:[1,0,1]
	s_cmp_eq_u64 s[44:45], exec
	s_cbranch_scc1 .LBB0_1304
	v_mul_hi_i32_i24_e32 v75, 0xac00, v213
	v_mul_i32_i24_e32 v74, 0xac00, v213
	v_lshl_add_u64 v[90:91], v[190:191], 0, v[74:75]
	global_load_dwordx4 v[74:77], v[90:91], off offset:16
	global_load_dwordx4 v[78:81], v[90:91], off
	global_load_dwordx4 v[86:89], v[90:91], off offset:528
	s_nop 0
	global_load_dwordx4 v[90:93], v[90:91], off offset:512
	v_add_u32_e32 v99, 0xffffe000, v212
	s_movk_i32 s4, 0x1fff
	v_lshrrev_b32_e32 v99, 12, v99
	v_cmp_gt_i32_e64 s[44:45], s4, v203
	v_lshrrev_b32_e32 v98, 11, v212
	v_add_u32_e32 v99, 4, v99
	v_cndmask_b32_e64 v98, v99, v98, s[44:45]
	v_cmp_eq_u32_e64 s[44:45], v98, v192
	s_movk_i32 s4, 0x1ffe
	s_waitcnt vmcnt(3)
	v_sub_f32_e32 v75, v75, v171
	s_waitcnt vmcnt(2)
	v_sub_f32_e32 v79, v79, v175
	v_sub_f32_e32 v78, v78, v174
	v_sub_f32_e32 v81, v81, v177
	v_sub_f32_e32 v80, v80, v176
	v_sub_f32_e32 v74, v74, v170
	v_sub_f32_e32 v77, v77, v173
	v_sub_f32_e32 v76, v76, v172
	s_waitcnt vmcnt(0)
	v_sub_f32_e32 v91, v91, v167
	v_sub_f32_e32 v90, v90, v166
	v_sub_f32_e32 v93, v93, v169
	v_sub_f32_e32 v92, v92, v168
	v_sub_f32_e32 v87, v87, v163
	v_sub_f32_e32 v86, v86, v162
	v_sub_f32_e32 v89, v89, v165
	v_sub_f32_e32 v88, v88, v164
	v_cndmask_b32_e64 v98, 1.0, 0, s[44:45]
	v_pk_fma_f32 v[136:137], v[98:99], v[80:81], v[136:137] op_sel_hi:[0,1,1]
	v_pk_fma_f32 v[134:135], v[98:99], v[78:79], v[134:135] op_sel_hi:[0,1,1]
	v_pk_fma_f32 v[128:129], v[98:99], v[76:77], v[128:129] op_sel_hi:[0,1,1]
	v_pk_fma_f32 v[126:127], v[98:99], v[74:75], v[126:127] op_sel_hi:[0,1,1]
	v_pk_fma_f32 v[148:149], v[98:99], v[92:93], v[148:149] op_sel_hi:[0,1,1]
	v_pk_fma_f32 v[146:147], v[98:99], v[90:91], v[146:147] op_sel_hi:[0,1,1]
	v_pk_fma_f32 v[140:141], v[98:99], v[88:89], v[140:141] op_sel_hi:[0,1,1]
	v_pk_fma_f32 v[138:139], v[98:99], v[86:87], v[138:139] op_sel_hi:[0,1,1]
	v_add_u32_e32 v99, 0xffffe000, v211
	v_lshrrev_b32_e32 v99, 12, v99
	v_cmp_gt_i32_e64 s[44:45], s4, v203
	v_lshrrev_b32_e32 v98, 11, v211
	v_add_u32_e32 v99, 4, v99
	v_cndmask_b32_e64 v98, v99, v98, s[44:45]
	v_cmp_eq_u32_e64 s[44:45], v98, v192
	s_movk_i32 s4, 0x1ffd
	v_pk_fma_f32 v[152:153], v[80:81], 0, v[152:153] op_sel_hi:[1,0,1]
	v_cndmask_b32_e64 v98, 1.0, 0, s[44:45]
	v_pk_fma_f32 v[120:121], v[98:99], v[80:81], v[120:121] op_sel_hi:[0,1,1]
	v_pk_fma_f32 v[118:119], v[98:99], v[78:79], v[118:119] op_sel_hi:[0,1,1]
	v_pk_fma_f32 v[96:97], v[98:99], v[76:77], v[96:97] op_sel_hi:[0,1,1]
	v_pk_fma_f32 v[94:95], v[98:99], v[74:75], v[94:95] op_sel_hi:[0,1,1]
	v_pk_fma_f32 v[132:133], v[98:99], v[92:93], v[132:133] op_sel_hi:[0,1,1]
	v_pk_fma_f32 v[130:131], v[98:99], v[90:91], v[130:131] op_sel_hi:[0,1,1]
	v_pk_fma_f32 v[124:125], v[98:99], v[88:89], v[124:125] op_sel_hi:[0,1,1]
	v_pk_fma_f32 v[122:123], v[98:99], v[86:87], v[122:123] op_sel_hi:[0,1,1]
	v_add_u32_e32 v99, 0xffffe000, v210
	v_lshrrev_b32_e32 v99, 12, v99
	v_cmp_gt_i32_e64 s[44:45], s4, v203
	v_lshrrev_b32_e32 v98, 11, v210
	v_add_u32_e32 v99, 4, v99
	v_cndmask_b32_e64 v98, v99, v98, s[44:45]
	v_cmp_eq_u32_e64 s[44:45], v98, v192
;     __device__ __forceinline__ void operator()(f32x4 (&acc)[2][2][4][2], const Unit& u, int wr, int wc, int fr, int fq) const {
;     ...
;                 for (int am = 0; am < 8; ++am) { const int ai = am >> 2, m = am & 3; int tok = tq + am; tok = tok < 0 ? 0 : (tok > TOK - 1 ? TOK - 1 : tok);
;                     const float mB = (batch_of(tok) == bA) ? 0.f : 1.f;
; #pragma unroll
;                     for (int bj = 0; bj < 2; ++bj)
; #pragma unroll
;                         for (int n = 0; n < 2; ++n) acc[ai][bj][m][n] += dv[bj][n] * mB; } } }
	s_movk_i32 s4, 0x1ffc
	v_pk_fma_f32 v[150:151], v[78:79], 0, v[150:151] op_sel_hi:[1,0,1]
	v_cndmask_b32_e64 v98, 1.0, 0, s[44:45]
	v_pk_fma_f32 v[72:73], v[98:99], v[80:81], v[72:73] op_sel_hi:[0,1,1]
	v_pk_fma_f32 v[70:71], v[98:99], v[78:79], v[70:71] op_sel_hi:[0,1,1]
	v_pk_fma_f32 v[64:65], v[98:99], v[76:77], v[64:65] op_sel_hi:[0,1,1]
	v_pk_fma_f32 v[62:63], v[98:99], v[74:75], v[62:63] op_sel_hi:[0,1,1]
	v_pk_fma_f32 v[116:117], v[98:99], v[92:93], v[116:117] op_sel_hi:[0,1,1]
	v_pk_fma_f32 v[114:115], v[98:99], v[90:91], v[114:115] op_sel_hi:[0,1,1]
	v_pk_fma_f32 v[84:85], v[98:99], v[88:89], v[84:85] op_sel_hi:[0,1,1]
	v_pk_fma_f32 v[82:83], v[98:99], v[86:87], v[82:83] op_sel_hi:[0,1,1]
	v_add_u32_e32 v99, 0xffffe000, v209
	v_lshrrev_b32_e32 v99, 12, v99
	v_cmp_gt_i32_e64 s[44:45], s4, v203
	v_lshrrev_b32_e32 v98, 11, v209
	v_add_u32_e32 v99, 4, v99
	v_cndmask_b32_e64 v98, v99, v98, s[44:45]
	v_cmp_eq_u32_e64 s[44:45], v98, v192
	s_movk_i32 s4, 0x1ffb
	v_pk_fma_f32 v[144:145], v[76:77], 0, v[144:145] op_sel_hi:[1,0,1]
	v_cndmask_b32_e64 v98, 1.0, 0, s[44:45]
	v_pk_fma_f32 v[56:57], v[98:99], v[80:81], v[56:57] op_sel_hi:[0,1,1]
	v_pk_fma_f32 v[54:55], v[98:99], v[78:79], v[54:55] op_sel_hi:[0,1,1]
	v_pk_fma_f32 v[48:49], v[98:99], v[76:77], v[48:49] op_sel_hi:[0,1,1]
	v_pk_fma_f32 v[46:47], v[98:99], v[74:75], v[46:47] op_sel_hi:[0,1,1]
	v_pk_fma_f32 v[68:69], v[98:99], v[92:93], v[68:69] op_sel_hi:[0,1,1]
	v_pk_fma_f32 v[66:67], v[98:99], v[90:91], v[66:67] op_sel_hi:[0,1,1]
	v_pk_fma_f32 v[60:61], v[98:99], v[88:89], v[60:61] op_sel_hi:[0,1,1]
	v_pk_fma_f32 v[58:59], v[98:99], v[86:87], v[58:59] op_sel_hi:[0,1,1]
	v_add_u32_e32 v99, 0xffffe000, v195
	v_lshrrev_b32_e32 v99, 12, v99
	v_cmp_gt_i32_e64 s[44:45], s4, v203
	v_lshrrev_b32_e32 v98, 11, v195
	v_add_u32_e32 v99, 4, v99
	v_cndmask_b32_e64 v98, v99, v98, s[44:45]
	v_cmp_eq_u32_e64 s[44:45], v98, v192
	s_movk_i32 s4, 0x1ffa
	v_pk_fma_f32 v[142:143], v[74:75], 0, v[142:143] op_sel_hi:[1,0,1]
	v_cndmask_b32_e64 v98, 1.0, 0, s[44:45]
	v_pk_fma_f32 v[40:41], v[98:99], v[80:81], v[40:41] op_sel_hi:[0,1,1]
	v_pk_fma_f32 v[38:39], v[98:99], v[78:79], v[38:39] op_sel_hi:[0,1,1]
	v_pk_fma_f32 v[32:33], v[98:99], v[76:77], v[32:33] op_sel_hi:[0,1,1]
	v_pk_fma_f32 v[30:31], v[98:99], v[74:75], v[30:31] op_sel_hi:[0,1,1]
	v_pk_fma_f32 v[52:53], v[98:99], v[92:93], v[52:53] op_sel_hi:[0,1,1]
	v_pk_fma_f32 v[50:51], v[98:99], v[90:91], v[50:51] op_sel_hi:[0,1,1]
	v_pk_fma_f32 v[44:45], v[98:99], v[88:89], v[44:45] op_sel_hi:[0,1,1]
	v_pk_fma_f32 v[42:43], v[98:99], v[86:87], v[42:43] op_sel_hi:[0,1,1]
	v_add_u32_e32 v99, 0xffffe000, v194
	v_lshrrev_b32_e32 v99, 12, v99
	v_cmp_gt_i32_e64 s[44:45], s4, v203
	v_lshrrev_b32_e32 v98, 11, v194
	v_add_u32_e32 v99, 4, v99
	v_cndmask_b32_e64 v98, v99, v98, s[44:45]
	v_cmp_eq_u32_e64 s[44:45], v98, v192
	v_pk_fma_f32 v[160:161], v[92:93], 0, v[160:161] op_sel_hi:[1,0,1]
	v_pk_fma_f32 v[158:159], v[90:91], 0, v[158:159] op_sel_hi:[1,0,1]
	v_cndmask_b32_e64 v98, 1.0, 0, s[44:45]
	v_pk_fma_f32 v[20:21], v[98:99], v[80:81], v[20:21] op_sel_hi:[0,1,1]
	v_pk_fma_f32 v[18:19], v[98:99], v[78:79], v[18:19] op_sel_hi:[0,1,1]
	v_pk_fma_f32 v[8:9], v[98:99], v[76:77], v[8:9] op_sel_hi:[0,1,1]
	v_pk_fma_f32 v[6:7], v[98:99], v[74:75], v[6:7] op_sel_hi:[0,1,1]
	v_pk_fma_f32 v[36:37], v[98:99], v[92:93], v[36:37] op_sel_hi:[0,1,1]
	v_pk_fma_f32 v[34:35], v[98:99], v[90:91], v[34:35] op_sel_hi:[0,1,1]
	v_pk_fma_f32 v[28:29], v[98:99], v[88:89], v[28:29] op_sel_hi:[0,1,1]
	v_pk_fma_f32 v[26:27], v[98:99], v[86:87], v[26:27] op_sel_hi:[0,1,1]
	v_add_u32_e32 v99, 0xffffe000, v193
	v_lshrrev_b32_e32 v99, 12, v99
	v_lshrrev_b32_e32 v98, 11, v193
	v_add_u32_e32 v99, 4, v99
	v_cndmask_b32_e64 v98, v99, v98, s[42:43]
	v_cmp_eq_u32_e64 s[42:43], v98, v192
	v_pk_fma_f32 v[156:157], v[88:89], 0, v[156:157] op_sel_hi:[1,0,1]
	v_pk_fma_f32 v[154:155], v[86:87], 0, v[154:155] op_sel_hi:[1,0,1]
	v_cndmask_b32_e64 v98, 1.0, 0, s[42:43]
	v_pk_fma_f32 v[24:25], v[98:99], v[80:81], v[24:25] op_sel_hi:[0,1,1]
	v_pk_fma_f32 v[22:23], v[98:99], v[78:79], v[22:23] op_sel_hi:[0,1,1]
	v_pk_fma_f32 v[12:13], v[98:99], v[76:77], v[12:13] op_sel_hi:[0,1,1]
	v_pk_fma_f32 v[10:11], v[98:99], v[74:75], v[10:11] op_sel_hi:[0,1,1]
	v_pk_fma_f32 v[16:17], v[98:99], v[92:93], v[16:17] op_sel_hi:[0,1,1]
	v_pk_fma_f32 v[14:15], v[98:99], v[90:91], v[14:15] op_sel_hi:[0,1,1]
	v_pk_fma_f32 v[4:5], v[98:99], v[88:89], v[4:5] op_sel_hi:[0,1,1]
	v_pk_fma_f32 v[2:3], v[98:99], v[86:87], v[2:3] op_sel_hi:[0,1,1]
; __device__ __forceinline__ unsigned cvt_pk_bf16(float lo, float hi) { unsigned r; asm volatile("v_cvt_pk_bf16_f32 %0, %1, %2" : "=v"(r) : "v"(lo), "v"(hi)); return r; }
;     __device__ __forceinline__ void operator()(f32x4 (&acc)[2][2][4][2], const Unit& u, int wr, int wc, int fr, int fq) const {
;     ...
;         f32x4 w0[2], w1[2], w2[2], cbv[2];
; #pragma unroll
;         for (int n = 0; n < 2; ++n) { w0[n] = LDG(f32x4, cw + f0 + 4 * n); w1[n] = LDG(f32x4, cw + DFF + f0 + 4 * n); w2[n] = LDG(f32x4, cw + 2 * DFF + f0 + 4 * n); cbv[n] = LDG(f32x4, cb + f0 + 4 * n); }
;         const int srcR = ((lane & 48) | ((fr + 15) & 15)) << 2, srcL = ((lane & 48) | ((fr + 1) & 15)) << 2;
;         f32x4 pvx[2], nvx[2];
; #pragma unroll
;         for (int n = 0; n < 2; ++n)
; #pragma unroll
;             for (int e = 0; e < 4; ++e) { pvx[n][e] = bperm(acc[1][0][3][n][e], srcR); nvx[n][e] = bperm(acc[0][0][0][n][e], srcL); }
;         const int tokl = tok0 + 8 * fr;
;         const int S = seq_len_of(tokl < 0 ? 0 : tokl);
; #pragma unroll
;         for (int am = 0; am < 8; ++am) {
;             const int ai = am >> 2, m = am & 3;
;             const int j = 8 * fr + am, tok = tokl + am, tpos = tok & (S - 1);
;             const bool first = (tpos == 0), lastt = (tpos == S - 1); const bool edge = __any(first || lastt);
;             const bool ok = (j >= 1) && (j <= 126) && (tok < TOK);
;             u32x4 w;
; #pragma unroll
;             for (int n = 0; n < 2; ++n) {
;                 f32x4 pv = (am == 0) ? pvx[n] : acc[(am - 1 < 0 ? 0 : am - 1) >> 2][0][(am - 1 < 0 ? 0 : am - 1) & 3][n];
;                 f32x4 nv = (am == 7) ? nvx[n] : acc[(am + 1 > 7 ? 7 : am + 1) >> 2][0][(am + 1 > 7 ? 7 : am + 1) & 3][n];
;                 f32x4 v = cbv[n] + w0[n] * pv + w1[n] * acc[ai][0][m][n] + w2[n] * nv;
;                 if (edge) {
;                     asm volatile("" ::: "memory");
;                     const f32x4 z = {0.f, 0.f, 0.f, 0.f}; const f32x4 pz = first ? z : pv, nz = lastt ? z : nv;
;                     v = cbv[n] + w0[n] * pz + w1[n] * acc[ai][0][m][n] + w2[n] * nz; }
;                 const f32x2 g0 = gelu_pk((f32x2){v[0], v[1]}), g1 = gelu_pk((f32x2){v[2], v[3]});
;                 const f32x4 bb = acc[ai][1][m][n];
;                 const unsigned lo = cvt_pk_bf16(g0.x * bb[0], g0.y * bb[1]), hi = cvt_pk_bf16(g1.x * bb[2], g1.y * bb[3]);
.LBB0_1304:
	v_lshl_or_b32 v166, s92, 7, v200
	v_ashrrev_i32_e32 v167, 31, v166
	s_nop 0
	s_nop 0
	s_nop 0
	s_nop 0
	v_mov_b32_e32 v162, 0xfff
	v_mov_b32_e32 v163, 0x7ff
	ds_bpermute_b32 v192, v198, v22
	ds_bpermute_b32 v174, v199, v150
	ds_bpermute_b32 v193, v198, v23
	ds_bpermute_b32 v175, v199, v151
	ds_bpermute_b32 v194, v198, v24
	ds_bpermute_b32 v172, v199, v152
	ds_bpermute_b32 v195, v198, v25
	ds_bpermute_b32 v173, v199, v153
	ds_bpermute_b32 v176, v198, v10
	ds_bpermute_b32 v170, v199, v142
	ds_bpermute_b32 v177, v198, v11
	ds_bpermute_b32 v171, v199, v143
	ds_bpermute_b32 v190, v198, v12
	ds_bpermute_b32 v168, v199, v144
	ds_bpermute_b32 v191, v198, v13
	ds_bpermute_b32 v169, v199, v145
	v_cndmask_b32_e32 v209, v162, v163, vcc
	v_and_b32_e32 v162, v209, v203
	v_cmp_eq_u32_e64 s[42:43], v162, v209
	s_cmp_lg_u64 s[42:43], 0
	v_mov_b64_e32 v[164:165], v[136:137]
	s_cselect_b64 s[4:5], -1, 0
	v_mov_b64_e32 v[162:163], v[134:135]
	s_mov_b64 vcc, s[42:43]
	s_cbranch_vccz .LBB0_1306
	v_cndmask_b32_e64 v165, v137, 0, s[42:43]
	v_cndmask_b32_e64 v164, v136, 0, s[42:43]
	v_cndmask_b32_e64 v163, v135, 0, s[42:43]
	v_cndmask_b32_e64 v162, v134, 0, s[42:43]
.LBB0_1306:
	s_waitcnt vmcnt(0) lgkmcnt(13)
	v_mov_b64_e32 v[74:75], v[240:241]
	v_mov_b64_e32 v[76:77], v[242:243]
	v_mov_b64_e32 v[78:79], v[244:245]
	v_mov_b64_e32 v[80:81], v[246:247]
	v_mov_b64_e32 v[90:91], v[248:249]
	v_mov_b64_e32 v[92:93], v[250:251]
	v_mov_b64_e32 v[98:99], v[222:223]
	v_mov_b64_e32 v[100:101], v[236:237]
	v_mov_b64_e32 v[110:111], v[252:253]
	v_mov_b32_e32 v112, v224
	v_mov_b32_e32 v113, v228
	v_mov_b32_e32 v86, v231
	v_mov_b32_e32 v87, v233
	v_mov_b32_e32 v88, v234
	v_mov_b32_e32 v89, v239
	v_pk_fma_f32 v[192:193], v[106:107], v[192:193], v[110:111]
	s_waitcnt lgkmcnt(9)
	v_pk_fma_f32 v[194:195], v[108:109], v[194:195], v[112:113]
	v_pk_fma_f32 v[192:193], v[150:151], v[98:99], v[192:193]
	v_pk_fma_f32 v[194:195], v[152:153], v[100:101], v[194:195]
	v_pk_fma_f32 v[162:163], v[162:163], v[102:103], v[192:193]
	v_pk_fma_f32 v[164:165], v[164:165], v[104:105], v[194:195]
	v_and_b32_e32 v193, 0x7fffffff, v163
	v_and_b32_e32 v192, 0x7fffffff, v162
	v_pk_fma_f32 v[194:195], v[192:193], s[78:79], 1.0 op_sel_hi:[1,0,0]
	v_mov_b64_e32 v[210:211], s[82:83]
	v_rcp_f32_e32 v194, v194
	v_rcp_f32_e32 v195, v195
	v_pk_mul_f32 v[216:217], v[162:163], v[162:163]
	s_andn2_b64 vcc, exec, s[4:5]
	v_pk_mul_f32 v[216:217], v[216:217], s[90:91] op_sel_hi:[1,0]
	v_pk_fma_f32 v[212:213], v[194:195], s[80:81], v[210:211] op_sel_hi:[1,0,0]
	v_exp_f32_e32 v216, v216
	v_pk_fma_f32 v[212:213], v[194:195], v[212:213], s[84:85] op_sel_hi:[1,1,0]
	v_exp_f32_e32 v217, v217
	v_pk_fma_f32 v[212:213], v[194:195], v[212:213], s[86:87] op_sel_hi:[1,1,0]
	s_nop 0
	v_pk_fma_f32 v[212:213], v[194:195], v[212:213], s[88:89] op_sel_hi:[1,1,0]
	s_nop 0
	v_pk_mul_f32 v[194:195], v[194:195], v[212:213]
	v_pk_mul_f32 v[212:213], v[164:165], v[164:165]
	v_pk_fma_f32 v[194:195], v[216:217], v[194:195], 0.5 op_sel_hi:[1,1,0] neg_lo:[1,0,0] neg_hi:[1,0,0]
	s_nop 0
	v_pk_mul_f32 v[192:193], v[192:193], v[194:195]
	s_nop 0
	v_pk_fma_f32 v[162:163], v[162:163], 0.5, v[192:193] op_sel_hi:[1,0,1]
	v_and_b32_e32 v193, 0x7fffffff, v165
	v_and_b32_e32 v192, 0x7fffffff, v164
	v_pk_fma_f32 v[194:195], v[192:193], s[78:79], 1.0 op_sel_hi:[1,0,0]
	v_mul_f32_e32 v158, v158, v162
	v_rcp_f32_e32 v194, v194
	v_rcp_f32_e32 v195, v195
	v_mul_f32_e32 v159, v159, v163
	v_cvt_pk_bf16_f32 v158, v158, v159
	v_pk_fma_f32 v[210:211], v[194:195], s[80:81], v[210:211] op_sel_hi:[1,0,0]
	s_nop 0
	v_pk_fma_f32 v[210:211], v[194:195], v[210:211], s[84:85] op_sel_hi:[1,1,0]
	s_nop 0
	v_pk_fma_f32 v[210:211], v[194:195], v[210:211], s[86:87] op_sel_hi:[1,1,0]
	s_nop 0
	v_pk_fma_f32 v[210:211], v[194:195], v[210:211], s[88:89] op_sel_hi:[1,1,0]
	s_nop 0
	v_pk_mul_f32 v[194:195], v[194:195], v[210:211]
	v_pk_mul_f32 v[210:211], v[212:213], s[90:91] op_sel_hi:[1,0]
	s_nop 0
	v_exp_f32_e32 v210, v210
	v_exp_f32_e32 v211, v211
	s_nop 0
	v_pk_fma_f32 v[194:195], v[210:211], v[194:195], 0.5 op_sel_hi:[1,1,0] neg_lo:[1,0,0] neg_hi:[1,0,0]
	s_nop 0
	v_pk_mul_f32 v[192:193], v[192:193], v[194:195]
	s_nop 0
	v_pk_fma_f32 v[164:165], v[164:165], 0.5, v[192:193] op_sel_hi:[1,0,1]
	s_nop 0
	v_mul_f32_e32 v159, v160, v164
	v_mul_f32_e32 v160, v161, v165
	v_cvt_pk_bf16_f32 v159, v159, v160
	v_mov_b64_e32 v[162:163], v[128:129]
	v_mov_b64_e32 v[160:161], v[126:127]
	s_cbranch_vccnz .LBB0_1308
	v_cndmask_b32_e64 v163, v129, 0, s[42:43]
	v_cndmask_b32_e64 v162, v128, 0, s[42:43]
	v_cndmask_b32_e64 v161, v127, 0, s[42:43]
	v_cndmask_b32_e64 v160, v126, 0, s[42:43]
